# v110 + attention prompt softmax row-sum with packed f32 adds (32 scalar adds -> 14 v_pk_add_f32 + 3)
# baseline (speedup 1.0000x reference)
.Lqk_done:
	ds_bpermute_b32 v13, v55, v10
	s_waitcnt lgkmcnt(0)
	v_max_f32_e32 v13, v13, v13
	v_max_f32_e32 v10, v10, v13
	ds_bpermute_b32 v13, v56, v10
	s_waitcnt vmcnt(0) lgkmcnt(0)
	v_max3_f32 v10, v10, v13, v37
	v_mul_f32_e32 v156, 0xbfb8aa3b, v10
	v_fmamk_f32 v14, v62, 0x3fb8aa3b, v156
	v_exp_f32_e32 v94, v14
	v_fmamk_f32 v14, v61, 0x3fb8aa3b, v156
	v_exp_f32_e32 v95, v14
	v_fmamk_f32 v14, v60, 0x3fb8aa3b, v156
	v_exp_f32_e32 v96, v14
	v_fmamk_f32 v14, v66, 0x3fb8aa3b, v156
	v_exp_f32_e32 v97, v14
	v_fmamk_f32 v14, v65, 0x3fb8aa3b, v156
	v_exp_f32_e32 v102, v14
	v_fmamk_f32 v14, v64, 0x3fb8aa3b, v156
	v_exp_f32_e32 v103, v14
	v_fmamk_f32 v14, v63, 0x3fb8aa3b, v156
	v_exp_f32_e32 v104, v14
	v_fmamk_f32 v14, v71, 0x3fb8aa3b, v156
	v_exp_f32_e32 v105, v14
	v_fmamk_f32 v14, v70, 0x3fb8aa3b, v156
	v_exp_f32_e32 v106, v14
	v_fmamk_f32 v14, v69, 0x3fb8aa3b, v156
	v_exp_f32_e32 v107, v14
	v_fmamk_f32 v14, v68, 0x3fb8aa3b, v156
	v_exp_f32_e32 v108, v14
	v_fmamk_f32 v14, v75, 0x3fb8aa3b, v156
	v_exp_f32_e32 v109, v14
	v_fmamk_f32 v14, v74, 0x3fb8aa3b, v156
	v_exp_f32_e32 v110, v14
	v_fmamk_f32 v14, v73, 0x3fb8aa3b, v156
	v_exp_f32_e32 v111, v14
	v_fmamk_f32 v14, v72, 0x3fb8aa3b, v156
	v_fmamk_f32 v13, v59, 0x3fb8aa3b, v156
	v_exp_f32_e32 v112, v14
	v_fmamk_f32 v14, v79, 0x3fb8aa3b, v156
	v_exp_f32_e32 v93, v13
	v_exp_f32_e32 v66, v14
	v_fmamk_f32 v14, v78, 0x3fb8aa3b, v156
	v_exp_f32_e32 v69, v14
	v_fmamk_f32 v14, v77, 0x3fb8aa3b, v156
	v_exp_f32_e32 v71, v14
	v_fmamk_f32 v14, v76, 0x3fb8aa3b, v156
	v_exp_f32_e32 v72, v14
	v_fmamk_f32 v14, v83, 0x3fb8aa3b, v156
	v_exp_f32_e32 v73, v14
	v_fmamk_f32 v14, v82, 0x3fb8aa3b, v156
	v_exp_f32_e32 v113, v14
	v_fmamk_f32 v14, v81, 0x3fb8aa3b, v156
	v_exp_f32_e32 v114, v14
	v_fmamk_f32 v14, v80, 0x3fb8aa3b, v156
	v_exp_f32_e32 v115, v14
	v_fmamk_f32 v14, v87, 0x3fb8aa3b, v156
	v_exp_f32_e32 v61, v14
	v_fmamk_f32 v14, v86, 0x3fb8aa3b, v156
	v_exp_f32_e32 v62, v14
	v_fmamk_f32 v14, v85, 0x3fb8aa3b, v156
	v_exp_f32_e32 v63, v14
	v_fmamk_f32 v14, v84, 0x3fb8aa3b, v156
	v_exp_f32_e32 v64, v14
	v_fmamk_f32 v14, v100, 0x3fb8aa3b, v156
	v_exp_f32_e32 v65, v14
	v_fmamk_f32 v14, v90, 0x3fb8aa3b, v156
	v_exp_f32_e32 v67, v14
	v_fmamk_f32 v14, v89, 0x3fb8aa3b, v156
	v_exp_f32_e32 v68, v14
	v_fmamk_f32 v14, v88, 0x3fb8aa3b, v156
	v_exp_f32_e32 v70, v14
	v_pk_add_f32 v[144:145], v[94:95], v[96:97]
	v_pk_add_f32 v[144:145], v[144:145], v[102:103]
	v_pk_add_f32 v[144:145], v[144:145], v[104:105]
	v_pk_add_f32 v[144:145], v[144:145], v[106:107]
	v_pk_add_f32 v[144:145], v[144:145], v[108:109]
	v_pk_add_f32 v[144:145], v[144:145], v[110:111]
	v_pk_add_f32 v[144:145], v[144:145], v[112:113]
	v_pk_add_f32 v[144:145], v[144:145], v[114:115]
	v_pk_add_f32 v[144:145], v[144:145], v[62:63]
	v_pk_add_f32 v[144:145], v[144:145], v[64:65]
	v_pk_add_f32 v[144:145], v[144:145], v[66:67]
	v_pk_add_f32 v[144:145], v[144:145], v[68:69]
	v_pk_add_f32 v[144:145], v[144:145], v[72:73]
	v_pk_add_f32 v[144:145], v[144:145], v[70:71]
	v_add_f32_e32 v13, v144, v145
	v_add_f32_e32 v13, v93, v13
	v_add_f32_e32 v14, v61, v13
	v_fmamk_f32 v13, v98, 0x3fb8aa3b, v156
	v_exp_f32_e32 v13, v13
	v_fmamk_f32 v17, v17, 0x3fb8aa3b, v156
	v_exp_f32_e32 v17, v17
	v_add_f32_e32 v15, v13, v14
	v_fmamk_f32 v14, v99, 0x3fb8aa3b, v156
	v_exp_f32_e32 v14, v14
	v_fmamk_f32 v11, v11, 0x3fb8aa3b, v156
	v_lshl_add_u32 v90, s37, 5, v49
	v_add_f32_e32 v16, v14, v15
	v_fmamk_f32 v15, v101, 0x3fb8aa3b, v156
	v_exp_f32_e32 v15, v15
	v_add_u32_e32 v78, 0x9000, v90
	ds_read2_b64 v[78:81], v78 offset1:4
	v_fmamk_f32 v12, v12, 0x3fb8aa3b, v156
	v_add_f32_e32 v58, v15, v16
	v_fmamk_f32 v16, v91, 0x3fb8aa3b, v156
	v_exp_f32_e32 v16, v16
	v_add_u32_e32 v82, 0xb000, v90
	v_add_u32_e32 v86, 0xd000, v90
	v_add_f32_e32 v58, v16, v58
	v_add_f32_e32 v59, v17, v58
	v_exp_f32_e32 v58, v11
	v_add_u32_e32 v90, 0xf000, v90
	v_lshl_add_u32 v98, s67, 5, v49
	v_cvt_pk_bf16_f32 v74, v93, v94
	v_add_f32_e32 v11, v58, v59
	v_exp_f32_e32 v59, v12
	v_fmamk_f32 v12, v92, 0x3fb8aa3b, v156
	ds_read2_b64 v[82:85], v82 offset0:32 offset1:36
	ds_read2_b64 v[86:89], v86 offset0:64 offset1:68
	ds_read2_b64 v[90:93], v90 offset0:96 offset1:100
	v_add_u32_e32 v94, 0x9000, v98
	v_cvt_pk_bf16_f32 v75, v95, v96
	v_cvt_pk_bf16_f32 v76, v97, v102
	ds_read2_b64 v[94:97], v94 offset1:4
	v_cvt_pk_bf16_f32 v77, v103, v104
	v_cvt_pk_bf16_f32 v62, v61, v62
	v_lshl_add_u32 v61, s77, 5, v49
	s_waitcnt lgkmcnt(4)
	v_mfma_f32_16x16x32_bf16 v[78:81], v[78:81], v[74:77], 0
	v_cvt_pk_bf16_f32 v63, v63, v64
	v_cvt_pk_bf16_f32 v64, v65, v67
	v_cvt_pk_bf16_f32 v65, v68, v70
	s_waitcnt lgkmcnt(3)
	v_mfma_f32_16x16x32_bf16 v[82:85], v[82:85], v[74:77], 0
	v_add_u32_e32 v70, 0xb000, v61
	v_exp_f32_e32 v60, v12
	s_waitcnt lgkmcnt(2)
	v_mfma_f32_16x16x32_bf16 v[86:89], v[86:89], v[74:77], 0
	v_cvt_pk_bf16_f32 v14, v13, v14
	v_lshl_add_u32 v13, s34, 5, v49
	v_add_f32_e32 v11, v59, v11
	s_waitcnt lgkmcnt(1)
	v_mfma_f32_16x16x32_bf16 v[74:77], v[90:93], v[74:77], 0
	v_cvt_pk_bf16_f32 v90, v105, v106
	v_cvt_pk_bf16_f32 v91, v107, v108
	v_cvt_pk_bf16_f32 v92, v109, v110
	v_cvt_pk_bf16_f32 v93, v111, v112
	v_cvt_pk_bf16_f32 v15, v15, v16
	v_cvt_pk_bf16_f32 v16, v17, v58
	s_waitcnt lgkmcnt(0)
	v_mfma_f32_16x16x32_bf16 v[78:81], v[94:97], v[90:93], v[78:81]
	v_add_u32_e32 v94, 0xb000, v98
	ds_read2_b64 v[94:97], v94 offset0:32 offset1:36
	v_add_u32_e32 v58, 0x9000, v13
	s_waitcnt lgkmcnt(0)
	v_mfma_f32_16x16x32_bf16 v[82:85], v[94:97], v[90:93], v[82:85]
	v_add_u32_e32 v94, 0xd000, v98
	ds_read2_b64 v[94:97], v94 offset0:64 offset1:68
	v_add_f32_e32 v11, v60, v11
	s_waitcnt lgkmcnt(0)
	v_mfma_f32_16x16x32_bf16 v[86:89], v[94:97], v[90:93], v[86:89]
	v_add_u32_e32 v94, 0xf000, v98
	ds_read2_b64 v[94:97], v94 offset0:96 offset1:100
	v_cvt_pk_bf16_f32 v17, v59, v60
	s_waitcnt lgkmcnt(0)
	v_mfma_f32_16x16x32_bf16 v[74:77], v[94:97], v[90:93], v[74:77]
	v_cvt_pk_bf16_f32 v90, v66, v69
	v_lshl_add_u32 v66, s76, 5, v49
	v_add_u32_e32 v69, 0x9000, v66
	ds_read2_b64 v[94:97], v69 offset1:4
	v_cvt_pk_bf16_f32 v91, v71, v72
	v_cvt_pk_bf16_f32 v92, v73, v113
	v_cvt_pk_bf16_f32 v93, v114, v115
	v_add_u32_e32 v69, 0xb000, v66
	ds_bpermute_b32 v12, v55, v11
	s_waitcnt lgkmcnt(1)
	v_mfma_f32_16x16x32_bf16 v[78:81], v[94:97], v[90:93], v[78:81]
	ds_read2_b64 v[94:97], v69 offset0:32 offset1:36
	v_add_u32_e32 v69, 0xd000, v66
	v_add_u32_e32 v66, 0xf000, v66
	s_waitcnt lgkmcnt(0)
	v_mfma_f32_16x16x32_bf16 v[82:85], v[94:97], v[90:93], v[82:85]
	ds_read2_b64 v[94:97], v69 offset0:64 offset1:68
	v_add_f32_e32 v11, v11, v12
	ds_bpermute_b32 v12, v56, v11
	s_waitcnt lgkmcnt(1)
	v_mfma_f32_16x16x32_bf16 v[86:89], v[94:97], v[90:93], v[86:89]
	ds_read2_b64 v[94:97], v66 offset0:96 offset1:100
	v_add_u32_e32 v66, 0x9000, v61
	ds_read2_b64 v[66:69], v66 offset1:4
	s_waitcnt lgkmcnt(1)
	v_mfma_f32_16x16x32_bf16 v[72:75], v[94:97], v[90:93], v[74:77]
	v_fmamk_f32 v10, v37, 0x3fb8aa3b, v156
	v_exp_f32_e32 v10, v10
	s_waitcnt lgkmcnt(0)
	v_mfma_f32_16x16x32_bf16 v[66:69], v[66:69], v[62:65], v[78:81]
	v_add_f32_e32 v11, v11, v12
	v_add_f32_e32 v10, v10, v11
	s_nop 0
	ds_read2_b64 v[76:79], v70 offset0:32 offset1:36
	v_add_u32_e32 v70, 0xd000, v61
	s_waitcnt lgkmcnt(0)
	v_mfma_f32_16x16x32_bf16 v[76:79], v[76:79], v[62:65], v[82:85]
	s_nop 2
	ds_read2_b64 v[80:83], v70 offset0:64 offset1:68
	v_add_u32_e32 v61, 0xf000, v61
	v_add_u32_e32 v70, 0xd000, v13
	s_waitcnt lgkmcnt(0)
	v_mfma_f32_16x16x32_bf16 v[80:83], v[80:83], v[62:65], v[86:89]
	s_nop 2
	ds_read2_b64 v[84:87], v61 offset0:96 offset1:100
	ds_read2_b64 v[58:61], v58 offset1:4
	v_div_scale_f32 v11, s[34:35], v10, v10, 1.0
	s_waitcnt lgkmcnt(0)
	v_mfma_f32_16x16x32_bf16 v[58:61], v[58:61], v[14:17], v[66:69]
	s_nop 2
	v_add_u32_e32 v66, 0xb000, v13
	ds_read2_b64 v[66:69], v66 offset0:32 offset1:36
	v_add_u32_e32 v13, 0xf000, v13
	v_mfma_f32_16x16x32_bf16 v[62:65], v[84:87], v[62:65], v[72:75]
	v_rcp_f32_e32 v12, v11
	s_mov_b32 s34, s36
	s_waitcnt lgkmcnt(0)
	v_mfma_f32_16x16x32_bf16 v[66:69], v[66:69], v[14:17], v[76:79]
	ds_read2_b64 v[70:73], v70 offset0:64 offset1:68
	s_nop 1
	ds_read2_b64 v[74:77], v13 offset0:96 offset1:100
	v_fma_f32 v13, -v11, v12, 1.0
	v_fmac_f32_e32 v12, v13, v12
	v_div_scale_f32 v13, vcc, 1.0, v10, 1.0
	s_waitcnt lgkmcnt(1)
	v_mfma_f32_16x16x32_bf16 v[70:73], v[70:73], v[14:17], v[80:83]
	s_waitcnt lgkmcnt(0)
	v_mfma_f32_16x16x32_bf16 v[14:17], v[74:77], v[14:17], v[62:65]
	s_nop 2
	v_mul_f32_e32 v62, v13, v12
	v_fma_f32 v63, -v11, v62, v13
	v_fmac_f32_e32 v62, v63, v12
	v_fma_f32 v11, -v11, v62, v13
	v_div_fmas_f32 v11, v11, v12, v62
	v_div_fixup_f32 v10, v11, v10, 1.0
	v_pk_mul_f32 v[12:13], v[60:61], v[10:11] op_sel_hi:[1,0]
	v_pk_mul_f32 v[58:59], v[58:59], v[10:11] op_sel_hi:[1,0]
	v_pk_mul_f32 v[16:17], v[10:11], v[16:17] op_sel_hi:[0,1]
	v_cvt_pk_bf16_f32 v58, v58, v59
	v_cvt_pk_bf16_f32 v59, v12, v13
	v_lshl_add_u64 v[12:13], v[38:39], 0, v[40:41]
	global_store_dwordx2 v[12:13], v[58:59], off
	v_pk_mul_f32 v[40:41], v[10:11], v[68:69] op_sel_hi:[0,1]
	v_pk_mul_f32 v[58:59], v[10:11], v[66:67] op_sel_hi:[0,1]
	v_cvt_pk_bf16_f32 v58, v58, v59
	v_cvt_pk_bf16_f32 v59, v40, v41
	global_store_dwordx2 v[12:13], v[58:59], off offset:32
	v_pk_mul_f32 v[40:41], v[10:11], v[72:73] op_sel_hi:[0,1]
	v_pk_mul_f32 v[58:59], v[10:11], v[70:71] op_sel_hi:[0,1]
	v_pk_mul_f32 v[10:11], v[10:11], v[14:15] op_sel_hi:[0,1]
	v_cvt_pk_bf16_f32 v58, v58, v59
	v_cvt_pk_bf16_f32 v59, v40, v41
	v_cvt_pk_bf16_f32 v10, v10, v11
	v_cvt_pk_bf16_f32 v11, v16, v17
	global_store_dwordx2 v[12:13], v[58:59], off offset:64
	global_store_dwordx2 v[12:13], v[10:11], off offset:96
	v_mov_b64_e32 v[16:17], v[8:9]
	v_mov_b64_e32 v[12:13], v[4:5]
	v_mov_b64_e32 v[14:15], v[6:7]
	v_mov_b64_e32 v[10:11], v[2:3]
	s_cbranch_scc1 .LBB0_1112
